# scan loop: superseded counted lgkmcnt waits removed (bit-identical) on top of v45
# speedup vs baseline: 1.0001x; 1.0001x over previous
; #define LAS __attribute__((address_space(3)))
; DI void hgrn_scan(ldsp lds, const bf16_t* QT, const bf16_t* KT, const bf16_t* KHT, const bf16_t* HVT, const float* DEC, bf16_t* HO, int vcu, int G) {
;     ...
;             ldsp qb_ = Lb + HS_QT + (tb * 32 + l31) * HS_QP + db * 64 + hh * 16; ldsp kb_ = Lb + HS_KT + l31 * HS_QP + db * 64 + hh * 16;
;             ldsp qr_ = Lb + HS_QT + (tb * 32 + l31) * HS_QP + 8 * hh + db * 64; ldsp vr_ = Lb + HS_VT + l31 * HS_P + 8 * hh;
;             const bf16x8 qv0 = *(const LAS bf16x8*)(qb_), qv1 = *(const LAS bf16x8*)(qb_ + 32), k00 = *(const LAS bf16x8*)(kb_), k01 = *(const LAS bf16x8*)(kb_ + 32);
;             const bf16x8 qa0 = lds_8x2(qr_, 16), qa1 = lds_8x2(qr_ + 32, 16), v00 = lds_8x2(vr_, 16), v01 = lds_8x2(vr_ + 32, 16);
;             bf16x8 k10 = k00, k11 = k01, v10 = v00, v11 = v01;
;             if (tb == 1) { k10 = *(const LAS bf16x8*)(kb_ + 32 * HS_QP); k11 = *(const LAS bf16x8*)(kb_ + 32 * HS_QP + 32); v10 = lds_8x2(vr_ + 64, 16); v11 = lds_8x2(vr_ + 96, 16); }
.LBB0_2075:
	s_or_b64 exec, exec, s[8:9]
	v_add_u32_e32 v28, v174, v147
	v_add_u32_e32 v28, 0xc800, v28
	ds_read_b128 v[88:91], v223
	ds_read_b128 v[84:87], v223 offset:32
	ds_read_b128 v[24:27], v224 offset:17408
	ds_read_b128 v[20:23], v224 offset:17440
	ds_read2_b64 v[16:19], v225 offset1:2
	ds_read2_b64 v[112:115], v225 offset0:4 offset1:6
	ds_read2_b64 v[108:111], v28 offset0:128 offset1:130
	ds_read2_b64 v[96:99], v28 offset0:132 offset1:134
	s_andn2_b64 s[8:9], exec, s[80:81]
	s_andn2_b64 vcc, exec, s[80:81]
	s_waitcnt lgkmcnt(0)
	s_cbranch_vccnz .LBB0_2077
	ds_read_b128 v[104:107], v224 offset:26112
	ds_read_b128 v[100:103], v224 offset:26144
	ds_read2_b64 v[92:95], v28 offset0:136 offset1:138
	ds_read2_b64 v[80:83], v28 offset0:140 offset1:142

; #define LAS __attribute__((address_space(3)))
; DI void hgrn_scan(ldsp lds, const bf16_t* QT, const bf16_t* KT, const bf16_t* KHT, const bf16_t* HVT, const float* DEC, bf16_t* HO, int vcu, int G) {
;     ...
;             ldsp qb_ = Lb + HS_QT + (tb * 32 + l31) * HS_QP + db * 64 + hh * 16; ldsp kb_ = Lb + HS_KT + l31 * HS_QP + db * 64 + hh * 16;
;             ldsp qr_ = Lb + HS_QT + (tb * 32 + l31) * HS_QP + 8 * hh + db * 64; ldsp vr_ = Lb + HS_VT + l31 * HS_P + 8 * hh;
;             const bf16x8 qv0 = *(const LAS bf16x8*)(qb_), qv1 = *(const LAS bf16x8*)(qb_ + 32), k00 = *(const LAS bf16x8*)(kb_), k01 = *(const LAS bf16x8*)(kb_ + 32);
;             const bf16x8 qa0 = lds_8x2(qr_, 16), qa1 = lds_8x2(qr_ + 32, 16), v00 = lds_8x2(vr_, 16), v01 = lds_8x2(vr_ + 32, 16);
;             bf16x8 k10 = k00, k11 = k01, v10 = v00, v11 = v01;
;             if (tb == 1) { k10 = *(const LAS bf16x8*)(kb_ + 32 * HS_QP); k11 = *(const LAS bf16x8*)(kb_ + 32 * HS_QP + 32); v10 = lds_8x2(vr_ + 64, 16); v11 = lds_8x2(vr_ + 96, 16); }
.LBB0_2093:
	v_add_u32_e32 v28, 0xe000, v225
	ds_read_b128 v[88:91], v223 offset:57344
	ds_read_b128 v[84:87], v223 offset:57376
	ds_read_b128 v[24:27], v227
	ds_read_b128 v[20:23], v227 offset:32
	ds_read2_b64 v[16:19], v28 offset1:2
	ds_read2_b64 v[112:115], v28 offset0:4 offset1:6
	v_add_u32_e32 v28, v176, v147
	ds_read2_b64 v[108:111], v28 offset1:2
	ds_read2_b64 v[96:99], v28 offset0:4 offset1:6
	s_and_b64 vcc, exec, s[8:9]
	s_waitcnt lgkmcnt(0)
	s_cbranch_vccnz .LBB0_2095
	ds_read_b128 v[100:103], v227 offset:8704
	ds_read_b128 v[104:107], v227 offset:8736
	ds_read2_b64 v[92:95], v28 offset0:8 offset1:10
	ds_read2_b64 v[80:83], v28 offset0:12 offset1:14
